# prompt attention loop: K/V LDS fragments prefetched ahead of MFMAs, row-max via v_max3 chains
# speedup vs baseline: 1.0182x; 1.0089x over previous
; #define LAS __attribute__((address_space(3)))
; __device__ __forceinline__ int crow(int r, int hi) { return (r & 3) + 8 * (r >> 2) + 4 * hi; }
; __device__ __forceinline__ void attn_tile(const LAS unsigned char* Kt, const LAS unsigned char* Vt, const LAS f32x4* ck, const bf16x8 (&qr)[4], const float cq2, const int kp0, const int qpos, const int qfirst, ...
;             f32x16 p0, p1;
;             const bool first = (m_run == -INFINITY);
;             const float cbase = first ? cq2 : cqm;
; #pragma unroll
;             for (int g = 0; g < 4; ++g) { const f32x4 c0 = ck[2 * g + hi], c1 = ck[8 + 2 * g + hi];
; #pragma unroll
;                 for (int i = 0; i < 4; ++i) { p0[4 * g + i] = cbase - c0[i]; p1[4 * g + i] = cbase - c1[i]; } }
; #pragma unroll
;             for (int d0 = 0; d0 < 4; ++d0) {
;                 const bf16x8 k0 = *(const LAS bf16x8*)(Kt + r32 * 144 + d0 * 32 + hi * 16), k1 = *(const LAS bf16x8*)(Kt + (32 + r32) * 144 + d0 * 32 + hi * 16);
;                 p0 = __builtin_amdgcn_mfma_f32_32x32x16_bf16(k0, qr[d0], p0, 0, 0, 0); p1 = __builtin_amdgcn_mfma_f32_32x32x16_bf16(k1, qr[d0], p1, 0, 0, 0); }
;             if (kp0 + 63 > qfirst) {
; #pragma unroll
;                 for (int r = 0; r < 16; ++r) { const int kk = kp0 + crow(r, hi); if (kk > qpos) p0[r] = -INFINITY; if (kk + 32 > qpos) p1[r] = -INFINITY; } }
.LBB0_526:
	v_cmp_le_i32_e32 vcc, s13, v101
	s_and_b32 s18, s17, 1
	s_and_b64 s[0:1], s[70:71], vcc
	s_and_saveexec_b64 s[6:7], s[0:1]
	s_cbranch_execz .LBB0_536
	v_lshl_add_u32 v62, s18, 8, v98
	s_mul_i32 s10, s18, 0x2400
	v_add_u32_e32 v196, s10, v105
	ds_read_b128 v[50:53], v62 offset:39040
	ds_read_b128 v[34:37], v62 offset:38912
	ds_read_b128 v[38:41], v62 offset:38944
	ds_read_b128 v[54:57], v62 offset:39072
	ds_read_b128 v[42:45], v62 offset:38976
	ds_read_b128 v[58:61], v62 offset:39104
	ds_read_b128 v[46:49], v62 offset:39008
	ds_read_b128 v[62:65], v62 offset:39136
	ds_read_b128 v[110:113], v196 offset:4608
	ds_read_b128 v[114:117], v196
	ds_read_b128 v[118:121], v196 offset:32
	ds_read_b128 v[200:203], v196 offset:4640
	ds_read_b128 v[204:207], v196 offset:64
	ds_read_b128 v[208:211], v196 offset:4672
	ds_read_b128 v[212:215], v196 offset:96
	v_cmp_eq_f32_e64 s[0:1], s37, v108
	v_cmp_neq_f32_e32 vcc, s37, v108
	s_nop 0
	v_cndmask_b32_e64 v109, v1, v100, s[0:1]
	s_waitcnt lgkmcnt(8)
	v_sub_f32_e32 v49, v109, v49
	v_sub_f32_e32 v48, v109, v48
	v_sub_f32_e32 v47, v109, v47
	v_sub_f32_e32 v46, v109, v46
	v_sub_f32_e32 v45, v109, v45
	v_sub_f32_e32 v44, v109, v44
	v_sub_f32_e32 v43, v109, v43
	v_sub_f32_e32 v42, v109, v42
	v_sub_f32_e32 v41, v109, v41
	v_sub_f32_e32 v40, v109, v40
	v_sub_f32_e32 v39, v109, v39
	v_sub_f32_e32 v38, v109, v38
	v_sub_f32_e32 v37, v109, v37
	v_sub_f32_e32 v36, v109, v36
	v_sub_f32_e32 v35, v109, v35
	v_sub_f32_e32 v34, v109, v34
	ds_read_b128 v[216:219], v196 offset:4704
	s_waitcnt lgkmcnt(8)
	v_sub_f32_e32 v65, v109, v65
	v_sub_f32_e32 v64, v109, v64
	v_sub_f32_e32 v63, v109, v63
	v_sub_f32_e32 v62, v109, v62
	v_sub_f32_e32 v61, v109, v61
	v_sub_f32_e32 v60, v109, v60
	v_sub_f32_e32 v59, v109, v59
	v_sub_f32_e32 v58, v109, v58
	v_sub_f32_e32 v57, v109, v57
	v_sub_f32_e32 v56, v109, v56
	v_sub_f32_e32 v55, v109, v55
	v_sub_f32_e32 v54, v109, v54
	v_sub_f32_e32 v53, v109, v53
	v_sub_f32_e32 v52, v109, v52
	v_sub_f32_e32 v51, v109, v51
	v_sub_f32_e32 v50, v109, v50
	s_add_i32 s0, s13, 63
	v_cmp_gt_i32_e64 s[0:1], s0, v99
	s_waitcnt lgkmcnt(7)
	v_mfma_f32_32x32x16_bf16 v[50:65], v[110:113], v[66:69], v[50:65]
	s_waitcnt lgkmcnt(6)
	v_mfma_f32_32x32x16_bf16 v[34:49], v[114:117], v[66:69], v[34:49]
	s_waitcnt lgkmcnt(5)
	v_mfma_f32_32x32x16_bf16 v[34:49], v[118:121], v[70:73], v[34:49]
	s_waitcnt lgkmcnt(4)
	v_mfma_f32_32x32x16_bf16 v[50:65], v[200:203], v[70:73], v[50:65]
	s_waitcnt lgkmcnt(3)
	v_mfma_f32_32x32x16_bf16 v[34:49], v[204:207], v[74:77], v[34:49]
	s_waitcnt lgkmcnt(2)
	v_mfma_f32_32x32x16_bf16 v[50:65], v[208:211], v[74:77], v[50:65]
	s_waitcnt lgkmcnt(1)
	v_mfma_f32_32x32x16_bf16 v[34:49], v[212:215], v[78:81], v[34:49]
	s_waitcnt lgkmcnt(0)
	v_mfma_f32_32x32x16_bf16 v[50:65], v[216:219], v[78:81], v[50:65]
	s_and_saveexec_b64 s[10:11], s[0:1]
	s_cbranch_execz .LBB0_529
	v_add_u32_e32 v109, s13, v102
	v_add_u32_e32 v110, 32, v109
	v_cmp_le_i32_e64 s[0:1], v110, v92
	v_add_u32_e32 v110, 33, v109
	s_nop 5
	v_cndmask_b32_e64 v50, v137, v50, s[0:1]
	v_cmp_lt_i32_e64 s[0:1], v109, v92
	s_nop 1
	v_cndmask_b32_e64 v35, v137, v35, s[0:1]
	v_cmp_le_i32_e64 s[0:1], v109, v92
	s_nop 1
	v_cndmask_b32_e64 v34, v137, v34, s[0:1]
	v_cmp_le_i32_e64 s[0:1], v110, v92
	v_add_u32_e32 v110, 2, v109
	s_nop 0
	v_cndmask_b32_e64 v51, v137, v51, s[0:1]
	v_cmp_le_i32_e64 s[0:1], v110, v92
	v_add_u32_e32 v110, 34, v109
	s_nop 0
	v_cndmask_b32_e64 v36, v137, v36, s[0:1]
	v_cmp_le_i32_e64 s[0:1], v110, v92
	v_add_u32_e32 v110, 3, v109
	s_nop 0
	v_cndmask_b32_e64 v52, v137, v52, s[0:1]
	v_cmp_le_i32_e64 s[0:1], v110, v92
	v_add_u32_e32 v110, 35, v109
	s_nop 0
	v_cndmask_b32_e64 v37, v137, v37, s[0:1]
	v_cmp_le_i32_e64 s[0:1], v110, v92
	v_add_u32_e32 v110, 8, v109
	s_nop 0
	v_cndmask_b32_e64 v53, v137, v53, s[0:1]
	v_cmp_le_i32_e64 s[0:1], v110, v92
	v_add_u32_e32 v110, 40, v109
	s_nop 0
	v_cndmask_b32_e64 v38, v137, v38, s[0:1]
	v_cmp_le_i32_e64 s[0:1], v110, v92
	v_add_u32_e32 v110, 9, v109
	s_nop 0
	v_cndmask_b32_e64 v54, v137, v54, s[0:1]
	v_cmp_le_i32_e64 s[0:1], v110, v92
	v_add_u32_e32 v110, 41, v109
	s_nop 0
	v_cndmask_b32_e64 v39, v137, v39, s[0:1]
	v_cmp_le_i32_e64 s[0:1], v110, v92
	v_add_u32_e32 v110, 10, v109
	s_nop 0
	v_cndmask_b32_e64 v55, v137, v55, s[0:1]
	v_cmp_le_i32_e64 s[0:1], v110, v92
	v_add_u32_e32 v110, 42, v109
	s_nop 0
	v_cndmask_b32_e64 v40, v137, v40, s[0:1]
	v_cmp_le_i32_e64 s[0:1], v110, v92
	v_add_u32_e32 v110, 11, v109
	s_nop 0
	v_cndmask_b32_e64 v56, v137, v56, s[0:1]
	v_cmp_le_i32_e64 s[0:1], v110, v92
	v_add_u32_e32 v110, 43, v109
	s_nop 0
	v_cndmask_b32_e64 v41, v137, v41, s[0:1]
	v_cmp_le_i32_e64 s[0:1], v110, v92
	v_add_u32_e32 v110, 16, v109
	s_nop 0
	v_cndmask_b32_e64 v57, v137, v57, s[0:1]
	v_cmp_le_i32_e64 s[0:1], v110, v92
	v_add_u32_e32 v110, 48, v109
	s_nop 0
	v_cndmask_b32_e64 v42, v137, v42, s[0:1]
	v_cmp_le_i32_e64 s[0:1], v110, v92
	v_add_u32_e32 v110, 17, v109
	s_nop 0
	v_cndmask_b32_e64 v58, v137, v58, s[0:1]
	v_cmp_le_i32_e64 s[0:1], v110, v92
	v_add_u32_e32 v110, 49, v109
	s_nop 0
	v_cndmask_b32_e64 v43, v137, v43, s[0:1]
	v_cmp_le_i32_e64 s[0:1], v110, v92
	v_add_u32_e32 v110, 18, v109
	s_nop 0
	v_cndmask_b32_e64 v59, v137, v59, s[0:1]
	v_cmp_le_i32_e64 s[0:1], v110, v92
	v_add_u32_e32 v110, 50, v109
	s_nop 0
	v_cndmask_b32_e64 v44, v137, v44, s[0:1]
	v_cmp_le_i32_e64 s[0:1], v110, v92
	v_add_u32_e32 v110, 19, v109
	s_nop 0
	v_cndmask_b32_e64 v60, v137, v60, s[0:1]
	v_cmp_le_i32_e64 s[0:1], v110, v92
	v_add_u32_e32 v110, 51, v109
	s_nop 0
	v_cndmask_b32_e64 v45, v137, v45, s[0:1]
	v_cmp_le_i32_e64 s[0:1], v110, v92
	v_add_u32_e32 v110, 24, v109
	s_nop 0
	v_cndmask_b32_e64 v61, v137, v61, s[0:1]
	v_cmp_le_i32_e64 s[0:1], v110, v92
	v_add_u32_e32 v110, 56, v109
	s_nop 0
	v_cndmask_b32_e64 v46, v137, v46, s[0:1]
	v_cmp_le_i32_e64 s[0:1], v110, v92
	v_add_u32_e32 v110, 25, v109
	s_nop 0
	v_cndmask_b32_e64 v62, v137, v62, s[0:1]
	v_cmp_le_i32_e64 s[0:1], v110, v92
	v_add_u32_e32 v110, 57, v109
	s_nop 0
	v_cndmask_b32_e64 v47, v137, v47, s[0:1]
	v_cmp_le_i32_e64 s[0:1], v110, v92
	v_add_u32_e32 v110, 26, v109
	s_nop 0
	v_cndmask_b32_e64 v63, v137, v63, s[0:1]
	v_cmp_le_i32_e64 s[0:1], v110, v92
	v_add_u32_e32 v110, 58, v109
	s_nop 0
	v_cndmask_b32_e64 v48, v137, v48, s[0:1]
	v_cmp_le_i32_e64 s[0:1], v110, v92
	v_add_u32_e32 v110, 27, v109
	v_add_u32_e32 v109, 59, v109
	v_cndmask_b32_e64 v64, v137, v64, s[0:1]
	v_cmp_le_i32_e64 s[0:1], v110, v92
	s_nop 1
	v_cndmask_b32_e64 v49, v137, v49, s[0:1]
	v_cmp_le_i32_e64 s[0:1], v109, v92
	s_nop 1
	v_cndmask_b32_e64 v65, v137, v65, s[0:1]
; __device__ __forceinline__ void attn_tile(const LAS unsigned char* Kt, const LAS unsigned char* Vt, const LAS f32x4* ck, const bf16x8 (&qr)[4], const float cq2, const int kp0, const int qpos, const int qfirst, ...
;     ...
;             float rm = fmaxf(p0[0], p1[0]);
; #pragma unroll
;             for (int r = 1; r < 16; ++r) rm = fmaxf(rm, fmaxf(p0[r], p1[r]));
;             rm = fmaxf(rm, __shfl_xor(rm, 32));
;             if (first) { m_run = rm; cqm = cq2 - rm;
; #pragma unroll
;                 for (int r = 0; r < 16; ++r) { p0[r] -= rm; p1[r] -= rm; } }
;             else if (__any(rm > 8.f)) { const float dl = fmaxf(rm, 0.f), alpha = __builtin_amdgcn_exp2f(-dl); m_run += dl; cqm -= dl; l_run *= alpha;
; #pragma unroll
;                 for (int r = 0; r < 16; ++r) { p0[r] -= dl; p1[r] -= dl; o0[r] *= alpha; o1[r] *= alpha; } }
.LBB0_529:
	s_or_b64 exec, exec, s[10:11]
	s_nop 8
	v_max3_f32 v109, v34, v35, v36
	v_max3_f32 v109, v109, v37, v38
	v_max3_f32 v109, v109, v39, v40
	v_max3_f32 v109, v109, v41, v42
	v_max3_f32 v109, v109, v43, v44
	v_max3_f32 v109, v109, v45, v46
	v_max3_f32 v109, v109, v47, v48
	v_max3_f32 v110, v50, v51, v52
	v_max3_f32 v110, v110, v53, v54
	v_max3_f32 v110, v110, v55, v56
	v_max3_f32 v110, v110, v57, v58
	v_max3_f32 v110, v110, v59, v60
	v_max3_f32 v110, v110, v61, v62
	v_max3_f32 v110, v110, v63, v64
	v_max3_f32 v109, v109, v110, v49
	v_max_f32_e32 v109, v109, v65
	v_and_b32_e32 v111, 64, v138
	v_xor_b32_e32 v110, 32, v138
	v_add_u32_e32 v111, 64, v111
	v_cmp_lt_i32_e64 s[0:1], v110, v111
	s_nop 1
	v_cndmask_b32_e64 v110, v138, v110, s[0:1]
	v_lshlrev_b32_e32 v110, 2, v110
	ds_bpermute_b32 v110, v110, v109
	s_waitcnt lgkmcnt(0)
	v_max_f32_e32 v110, v110, v110
	v_max_f32_e32 v109, v109, v110
	s_and_saveexec_b64 s[0:1], vcc
	s_xor_b64 s[0:1], exec, s[0:1]
	s_cbranch_execz .LBB0_533
	s_mov_b32 s10, 0x41000000
	v_cmp_lt_f32_e32 vcc, s10, v109
	s_cbranch_vccz .LBB0_532
	v_max_f32_e32 v109, v109, v109
	v_max_f32_e32 v109, 0, v109
	v_exp_f32_e64 v110, -v109
	v_add_f32_e32 v108, v108, v109
	v_sub_f32_e32 v1, v1, v109
	v_sub_f32_e32 v49, v49, v109
	v_mul_f32_e32 v103, v103, v110
	v_sub_f32_e32 v48, v48, v109
	v_sub_f32_e32 v47, v47, v109
	v_sub_f32_e32 v46, v46, v109
	v_sub_f32_e32 v45, v45, v109
	v_sub_f32_e32 v44, v44, v109
	v_sub_f32_e32 v43, v43, v109
	v_sub_f32_e32 v42, v42, v109
	v_sub_f32_e32 v41, v41, v109
	v_sub_f32_e32 v40, v40, v109
	v_sub_f32_e32 v39, v39, v109
	v_sub_f32_e32 v38, v38, v109
	v_sub_f32_e32 v37, v37, v109
	v_sub_f32_e32 v36, v36, v109
	v_sub_f32_e32 v35, v35, v109
	v_sub_f32_e32 v34, v34, v109
	v_sub_f32_e32 v65, v65, v109
	v_sub_f32_e32 v64, v64, v109
	v_sub_f32_e32 v63, v63, v109
	v_sub_f32_e32 v62, v62, v109
	v_sub_f32_e32 v61, v61, v109
	v_sub_f32_e32 v60, v60, v109
	v_sub_f32_e32 v59, v59, v109
	v_sub_f32_e32 v58, v58, v109
	v_sub_f32_e32 v57, v57, v109
	v_sub_f32_e32 v56, v56, v109
	v_sub_f32_e32 v55, v55, v109
	v_sub_f32_e32 v54, v54, v109
	v_sub_f32_e32 v53, v53, v109
	v_sub_f32_e32 v52, v52, v109
	v_sub_f32_e32 v51, v51, v109
	v_sub_f32_e32 v50, v50, v109
	v_pk_mul_f32 v[32:33], v[32:33], v[110:111] op_sel_hi:[1,0]
	v_pk_mul_f32 v[30:31], v[30:31], v[110:111] op_sel_hi:[1,0]
	v_pk_mul_f32 v[28:29], v[28:29], v[110:111] op_sel_hi:[1,0]
	v_pk_mul_f32 v[26:27], v[26:27], v[110:111] op_sel_hi:[1,0]
	v_pk_mul_f32 v[24:25], v[24:25], v[110:111] op_sel_hi:[1,0]
	v_pk_mul_f32 v[22:23], v[22:23], v[110:111] op_sel_hi:[1,0]
	v_pk_mul_f32 v[20:21], v[20:21], v[110:111] op_sel_hi:[1,0]
	v_pk_mul_f32 v[18:19], v[18:19], v[110:111] op_sel_hi:[1,0]
	v_pk_mul_f32 v[16:17], v[16:17], v[110:111] op_sel_hi:[1,0]
	v_pk_mul_f32 v[14:15], v[14:15], v[110:111] op_sel_hi:[1,0]
	v_pk_mul_f32 v[12:13], v[12:13], v[110:111] op_sel_hi:[1,0]
	v_pk_mul_f32 v[10:11], v[10:11], v[110:111] op_sel_hi:[1,0]
	v_pk_mul_f32 v[8:9], v[8:9], v[110:111] op_sel_hi:[1,0]
	v_pk_mul_f32 v[6:7], v[6:7], v[110:111] op_sel_hi:[1,0]
	v_pk_mul_f32 v[4:5], v[4:5], v[110:111] op_sel_hi:[1,0]
	v_pk_mul_f32 v[2:3], v[2:3], v[110:111] op_sel_hi:[1,0]

; #define LAS __attribute__((address_space(3)))
; __device__ __forceinline__ unsigned cvt_pk_bf16(float lo, float hi) { unsigned r; asm volatile("v_cvt_pk_bf16_f32 %0, %1, %2" : "=v"(r) : "v"(lo), "v"(hi)); return r; }
; __device__ __forceinline__ void attn_tile(const LAS unsigned char* Kt, const LAS unsigned char* Vt, const LAS f32x4* ck, const bf16x8 (&qr)[4], const float cq2, const int kp0, const int qpos, const int qfirst, ...
;     ...
;             float ps = 0.f;
; #pragma unroll
;             for (int r = 0; r < 16; ++r) { p0[r] = __builtin_amdgcn_exp2f(p0[r]); p1[r] = __builtin_amdgcn_exp2f(p1[r]); ps += p0[r] + p1[r]; }
;             l_run += ps;
;             bf16x8 pa[4];
;             { u32x4 w;
;               w.x = cvt_pk_bf16(p0[0], p0[1]); w.y = cvt_pk_bf16(p0[2], p0[3]); w.z = cvt_pk_bf16(p0[4], p0[5]); w.w = cvt_pk_bf16(p0[6], p0[7]); pa[0] = __builtin_bit_cast(bf16x8, w);
;               w.x = cvt_pk_bf16(p0[8], p0[9]); w.y = cvt_pk_bf16(p0[10], p0[11]); w.z = cvt_pk_bf16(p0[12], p0[13]); w.w = cvt_pk_bf16(p0[14], p0[15]); pa[1] = __builtin_bit_cast(bf16x8, w);
;               w.x = cvt_pk_bf16(p1[0], p1[1]); w.y = cvt_pk_bf16(p1[2], p1[3]); w.z = cvt_pk_bf16(p1[4], p1[5]); w.w = cvt_pk_bf16(p1[6], p1[7]); pa[2] = __builtin_bit_cast(bf16x8, w);
;               w.x = cvt_pk_bf16(p1[8], p1[9]); w.y = cvt_pk_bf16(p1[10], p1[11]); w.z = cvt_pk_bf16(p1[12], p1[13]); w.w = cvt_pk_bf16(p1[14], p1[15]); pa[3] = __builtin_bit_cast(bf16x8, w); }
;             const LAS unsigned char* vbase = Vt + (4 * hi + ((lane & 15) >> 2)) * 160 + ((lane >> 4) & 1) * 32 + (lane & 3) * 8;
; #pragma unroll
;             for (int kk = 0; kk < 4; ++kk) {
; #pragma unroll
;                 for (int dh = 0; dh < 2; ++dh) {
;                     const v4i16_t lo = __builtin_amdgcn_ds_read_tr16_b64_v4i16((LAS v4i16_t*)(vbase + kk * 16 * 160 + dh * 64));
;                     const v4i16_t hv = __builtin_amdgcn_ds_read_tr16_b64_v4i16((LAS v4i16_t*)(vbase + kk * 16 * 160 + 8 * 160 + dh * 64));
;                     const bf16x8 vf = (bf16x8){lo[0], lo[1], lo[2], lo[3], hv[0], hv[1], hv[2], hv[3]};
;                     if (dh == 0) o0 = __builtin_amdgcn_mfma_f32_32x32x16_bf16(vf, pa[kk], o0, 0, 0, 0); else o1 = __builtin_amdgcn_mfma_f32_32x32x16_bf16(vf, pa[kk], o1, 0, 0, 0); } }
.LBB0_535:
	s_or_b64 exec, exec, s[0:1]
	s_mul_i32 s32, s18, 0x2800
	v_add_u32_e32 v199, s32, v104
	ds_read_b64_tr_b16 v[220:221], v199 offset:18432
	ds_read_b64_tr_b16 v[222:223], v199 offset:19712
	ds_read_b64_tr_b16 v[224:225], v199 offset:18496
	ds_read_b64_tr_b16 v[226:227], v199 offset:19776
	ds_read_b64_tr_b16 v[228:229], v199 offset:20992
	ds_read_b64_tr_b16 v[230:231], v199 offset:22272
	ds_read_b64_tr_b16 v[232:233], v199 offset:21056
	ds_read_b64_tr_b16 v[234:235], v199 offset:22336
	ds_read_b64_tr_b16 v[236:237], v199 offset:23552
	ds_read_b64_tr_b16 v[238:239], v199 offset:24832
	ds_read_b64_tr_b16 v[240:241], v199 offset:23616
	ds_read_b64_tr_b16 v[242:243], v199 offset:24896
	ds_read_b64_tr_b16 v[244:245], v199 offset:26112
	ds_read_b64_tr_b16 v[246:247], v199 offset:27392
	v_exp_f32_e32 v109, v34
	v_exp_f32_e32 v112, v50
	v_exp_f32_e32 v113, v35
	v_exp_f32_e32 v114, v51
	v_exp_f32_e32 v115, v36
	v_exp_f32_e32 v116, v52
	v_exp_f32_e32 v117, v37
	v_exp_f32_e32 v118, v53
	v_add_f32_e32 v34, v112, v109
	v_add_f32_e32 v34, 0, v34
	v_add_f32_e32 v35, v114, v113
	v_add_f32_e32 v34, v35, v34
	v_add_f32_e32 v35, v116, v115
	v_add_f32_e32 v34, v35, v34
	v_add_f32_e32 v35, v118, v117
	v_add_f32_e32 v50, v35, v34
	v_exp_f32_e32 v35, v38
	v_exp_f32_e32 v37, v54
	v_exp_f32_e32 v34, v39
	v_exp_f32_e32 v36, v55
	v_exp_f32_e32 v51, v40
	v_exp_f32_e32 v53, v56
	v_exp_f32_e32 v52, v57
	v_pk_add_f32 v[38:39], v[36:37], v[34:35]
	v_exp_f32_e32 v55, v42
	v_add_f32_e32 v39, v39, v50
	v_exp_f32_e32 v50, v41
	v_add_f32_e32 v54, v38, v39
	v_exp_f32_e32 v57, v58
	v_exp_f32_e32 v56, v59
	v_pk_add_f32 v[38:39], v[52:53], v[50:51]
	v_exp_f32_e32 v59, v44
	v_add_f32_e32 v39, v39, v54
	v_exp_f32_e32 v54, v43
	v_exp_f32_e32 v111, v60
	v_exp_f32_e32 v58, v45
	v_exp_f32_e32 v110, v61
	v_add_f32_e32 v40, v38, v39
	v_pk_add_f32 v[38:39], v[56:57], v[54:55]
	v_exp_f32_e32 v45, v46
	v_exp_f32_e32 v61, v62
	v_exp_f32_e32 v44, v47
	v_exp_f32_e32 v60, v63
	v_add_f32_e32 v39, v39, v40
	v_add_f32_e32 v40, v38, v39
	v_pk_add_f32 v[38:39], v[110:111], v[58:59]
	v_exp_f32_e32 v47, v48
	v_exp_f32_e32 v63, v64
	v_exp_f32_e32 v46, v49
	v_exp_f32_e32 v62, v65
	v_add_f32_e32 v39, v39, v40
	v_add_f32_e32 v40, v38, v39
	v_pk_add_f32 v[38:39], v[60:61], v[44:45]
	s_mul_i32 s0, s18, 0x2800
	v_add_f32_e32 v39, v39, v40
	v_add_f32_e32 v40, v38, v39
	v_pk_add_f32 v[38:39], v[62:63], v[46:47]
	s_nop 0
	v_add_f32_e32 v39, v39, v40
	v_add_f32_e32 v38, v38, v39
	v_add_f32_e32 v103, v103, v38
	v_cvt_pk_bf16_f32 v38, v109, v113
	v_cvt_pk_bf16_f32 v39, v115, v117
	v_cvt_pk_bf16_f32 v40, v35, v34
	v_cvt_pk_bf16_f32 v41, v51, v50
	v_cvt_pk_bf16_f32 v42, v55, v54
	s_waitcnt lgkmcnt(13)
	ds_read_b64_tr_b16 v[248:249], v199 offset:26176
	ds_read_b64_tr_b16 v[250:251], v199 offset:27456
	v_cvt_pk_bf16_f32 v43, v59, v58
	v_cvt_pk_bf16_f32 v44, v45, v44
	v_cvt_pk_bf16_f32 v45, v47, v46
	v_cvt_pk_bf16_f32 v46, v112, v114
	v_cvt_pk_bf16_f32 v47, v116, v118
	v_cvt_pk_bf16_f32 v48, v37, v36
	v_cvt_pk_bf16_f32 v49, v53, v52
	v_cvt_pk_bf16_f32 v34, v57, v56
	v_cvt_pk_bf16_f32 v35, v111, v110
	v_cvt_pk_bf16_f32 v36, v61, v60
	v_cvt_pk_bf16_f32 v37, v63, v62
	s_waitcnt lgkmcnt(0)
	v_mfma_f32_32x32x16_bf16 v[18:33], v[220:223], v[38:41], v[18:33]
	v_mfma_f32_32x32x16_bf16 v[2:17], v[224:227], v[38:41], v[2:17]
	v_mfma_f32_32x32x16_bf16 v[18:33], v[228:231], v[42:45], v[18:33]
	v_mfma_f32_32x32x16_bf16 v[2:17], v[232:235], v[42:45], v[2:17]
	v_mfma_f32_32x32x16_bf16 v[18:33], v[236:239], v[46:49], v[18:33]
	v_mfma_f32_32x32x16_bf16 v[2:17], v[240:243], v[46:49], v[2:17]
	v_mfma_f32_32x32x16_bf16 v[18:33], v[244:247], v[34:37], v[18:33]
	v_mfma_f32_32x32x16_bf16 v[2:17], v[248:251], v[34:37], v[2:17]
